# F + barrier direct TOPGEN poll + unit-boundary vmcnt(0) moved behind the accumulator clears (clears run under the store drain)
# speedup vs baseline: 1.0057x; 1.0019x over previous
; template <class Epi, class Sched, bool ALIGN_EPI = false, bool SP2 = false>
; __device__ __forceinline__ void gemm_phase(PG8_LAS unsigned char* lds, const Gemm g, const Sched& S, const Epi& E) {
;     ...
;         const char* nA = has_next ? (const char*)g.A + (size_t)nxt.pm * tstep : cA; const char* nB = has_next ? (const char*)g.Bt + (size_t)nxt.pn * tstep : cB;
;         for (int t = 0; t < nt; t += 2) {
;             const bool last = (t == nt - 2);
;             const char* a1 = cA + (size_t)(t + 1) * kstep;
;             const char* a2 = last ? nA : cA + (size_t)(t + 2) * kstep; const char* b2 = last ? nB : cB + (size_t)(t + 2) * kstep;
;     ...
;         for (int a = 0; a < 2; ++a)
; #pragma unroll
;             for (int b = 0; b < 2; ++b)
; #pragma unroll
;                 for (int m = 0; m < 4; ++m)
; #pragma unroll
;                     for (int n = 0; n < 2; ++n) acc[a][b][m][n] = (f32x4){0.f, 0.f, 0.f, 0.f};
.LBB0_164:
	s_ashr_i32 s47, s46, 31
	s_lshl_b64 s[58:59], s[46:47], 20
	s_add_u32 s74, s12, s58
	s_addc_u32 s75, s13, s59
	s_and_b64 s[58:59], s[40:41], exec
	s_cselect_b32 s47, s75, s43
	s_cselect_b32 s55, s74, s42
	s_ashr_i32 s45, s44, 31
	s_lshl_b64 s[58:59], s[44:45], 20
	v_readlane_b32 s68, v255, 52
	v_readlane_b32 s69, v255, 53
	s_add_u32 s76, s68, s58
	s_addc_u32 s77, s69, s59
	s_and_b64 s[58:59], s[40:41], exec
	s_cselect_b32 s45, s77, s79
	s_cselect_b32 s58, s76, s78
	s_add_u32 s42, s42, 0x80080
	s_addc_u32 s43, s43, 0
	s_add_u32 s59, s78, 0x100
	v_mov_b32_e32 v0, 0
	s_addc_u32 s63, s79, 0
	s_mov_b32 s71, -2
	v_mov_b32_e32 v1, v0
	v_mov_b32_e32 v2, v0
	v_mov_b32_e32 v3, v0
	v_mov_b32_e32 v4, v0
	v_mov_b32_e32 v5, v0
	v_mov_b32_e32 v6, v0
	v_mov_b32_e32 v7, v0
	v_mov_b32_e32 v16, v0
	v_mov_b32_e32 v17, v0
	v_mov_b32_e32 v18, v0
	v_mov_b32_e32 v19, v0
	v_mov_b32_e32 v20, v0
	v_mov_b32_e32 v21, v0
	v_mov_b32_e32 v22, v0
	v_mov_b32_e32 v23, v0
	v_mov_b32_e32 v32, v0
	v_mov_b32_e32 v33, v0
	v_mov_b32_e32 v34, v0
	v_mov_b32_e32 v35, v0
	v_mov_b32_e32 v36, v0
	v_mov_b32_e32 v37, v0
	v_mov_b32_e32 v38, v0
	v_mov_b32_e32 v39, v0
	v_mov_b32_e32 v48, v0
	v_mov_b32_e32 v49, v0
	v_mov_b32_e32 v50, v0
	v_mov_b32_e32 v51, v0
	v_mov_b32_e32 v52, v0
	v_mov_b32_e32 v53, v0
	v_mov_b32_e32 v54, v0
	v_mov_b32_e32 v55, v0
	v_mov_b32_e32 v8, v0
	v_mov_b32_e32 v9, v0
	v_mov_b32_e32 v10, v0
	v_mov_b32_e32 v11, v0
	v_mov_b32_e32 v12, v0
	v_mov_b32_e32 v13, v0
	v_mov_b32_e32 v14, v0
	v_mov_b32_e32 v15, v0
	v_mov_b32_e32 v24, v0
	v_mov_b32_e32 v25, v0
	v_mov_b32_e32 v26, v0
	v_mov_b32_e32 v27, v0
	v_mov_b32_e32 v28, v0
	v_mov_b32_e32 v29, v0
	v_mov_b32_e32 v30, v0
	v_mov_b32_e32 v31, v0
	v_mov_b32_e32 v40, v0
	v_mov_b32_e32 v41, v0
	v_mov_b32_e32 v42, v0
	v_mov_b32_e32 v43, v0
	v_mov_b32_e32 v44, v0
	v_mov_b32_e32 v45, v0
	v_mov_b32_e32 v46, v0
	v_mov_b32_e32 v47, v0
	v_mov_b32_e32 v56, v0
	v_mov_b32_e32 v57, v0
	v_mov_b32_e32 v58, v0
	v_mov_b32_e32 v59, v0
	v_mov_b32_e32 v60, v0
	v_mov_b32_e32 v61, v0
	v_mov_b32_e32 v62, v0
	v_mov_b32_e32 v63, v0
	v_mov_b32_e32 v64, v0
	v_mov_b32_e32 v65, v0
	v_mov_b32_e32 v66, v0
	v_mov_b32_e32 v67, v0
	v_mov_b32_e32 v68, v0
	v_mov_b32_e32 v69, v0
	v_mov_b32_e32 v70, v0
	v_mov_b32_e32 v71, v0
	v_mov_b32_e32 v80, v0
	v_mov_b32_e32 v81, v0
	v_mov_b32_e32 v82, v0
	v_mov_b32_e32 v83, v0
	v_mov_b32_e32 v84, v0
	v_mov_b32_e32 v85, v0
	v_mov_b32_e32 v86, v0
	v_mov_b32_e32 v87, v0
	v_mov_b32_e32 v96, v0
	v_mov_b32_e32 v97, v0
	v_mov_b32_e32 v98, v0
	v_mov_b32_e32 v99, v0
	v_mov_b32_e32 v100, v0
	v_mov_b32_e32 v101, v0
	v_mov_b32_e32 v102, v0
	v_mov_b32_e32 v103, v0
	v_mov_b32_e32 v112, v0
	v_mov_b32_e32 v113, v0
	v_mov_b32_e32 v114, v0
	v_mov_b32_e32 v115, v0
	v_mov_b32_e32 v116, v0
	v_mov_b32_e32 v117, v0
	v_mov_b32_e32 v118, v0
	v_mov_b32_e32 v119, v0
	v_mov_b32_e32 v72, v0
	v_mov_b32_e32 v73, v0
	v_mov_b32_e32 v74, v0
	v_mov_b32_e32 v75, v0
	v_mov_b32_e32 v76, v0
	v_mov_b32_e32 v77, v0
	v_mov_b32_e32 v78, v0
	v_mov_b32_e32 v79, v0
	v_mov_b32_e32 v88, v0
	v_mov_b32_e32 v89, v0
	v_mov_b32_e32 v90, v0
	v_mov_b32_e32 v91, v0
	v_mov_b32_e32 v92, v0
	v_mov_b32_e32 v93, v0
	v_mov_b32_e32 v94, v0
	v_mov_b32_e32 v95, v0
	v_mov_b32_e32 v104, v0
	v_mov_b32_e32 v105, v0
	v_mov_b32_e32 v106, v0
	v_mov_b32_e32 v107, v0
	v_mov_b32_e32 v108, v0
	v_mov_b32_e32 v109, v0
	v_mov_b32_e32 v110, v0
	v_mov_b32_e32 v111, v0
	v_mov_b32_e32 v120, v0
	v_mov_b32_e32 v121, v0
	v_mov_b32_e32 v122, v0
	v_mov_b32_e32 v123, v0
	v_mov_b32_e32 v124, v0
	v_mov_b32_e32 v125, v0
	v_mov_b32_e32 v126, v0
	v_mov_b32_e32 v127, v0
	s_waitcnt vmcnt(0)

; template <class Epi, class Sched, bool ALIGN_EPI = false, bool SP2 = false>
; __device__ __forceinline__ void gemm_phase(PG8_LAS unsigned char* lds, const Gemm g, const Sched& S, const Epi& E) {
;     ...
;         for (int a = 0; a < 2; ++a)
; #pragma unroll
;             for (int b = 0; b < 2; ++b)
; #pragma unroll
;                 for (int m = 0; m < 4; ++m)
; #pragma unroll
;                     for (int n = 0; n < 2; ++n) acc[a][b][m][n] = (f32x4){0.f, 0.f, 0.f, 0.f};
;         cur = nxt; cA = nA; cB = nB; ++ui;
.LBB0_217:
	s_add_u32 s44, s86, 0x80
	s_addc_u32 s45, s87, 0
	s_add_u32 s86, s46, 0x100
	v_mov_b32_e32 v0, 0
	s_addc_u32 s87, s47, 0
	s_mov_b32 s46, 0
	v_mov_b32_e32 v1, v0
	v_mov_b32_e32 v2, v0
	v_mov_b32_e32 v3, v0
	v_mov_b32_e32 v4, v0
	v_mov_b32_e32 v5, v0
	v_mov_b32_e32 v6, v0
	v_mov_b32_e32 v7, v0
	v_mov_b32_e32 v16, v0
	v_mov_b32_e32 v17, v0
	v_mov_b32_e32 v18, v0
	v_mov_b32_e32 v19, v0
	v_mov_b32_e32 v20, v0
	v_mov_b32_e32 v21, v0
	v_mov_b32_e32 v22, v0
	v_mov_b32_e32 v23, v0
	v_mov_b32_e32 v32, v0
	v_mov_b32_e32 v33, v0
	v_mov_b32_e32 v34, v0
	v_mov_b32_e32 v35, v0
	v_mov_b32_e32 v36, v0
	v_mov_b32_e32 v37, v0
	v_mov_b32_e32 v38, v0
	v_mov_b32_e32 v39, v0
	v_mov_b32_e32 v48, v0
	v_mov_b32_e32 v49, v0
	v_mov_b32_e32 v50, v0
	v_mov_b32_e32 v51, v0
	v_mov_b32_e32 v52, v0
	v_mov_b32_e32 v53, v0
	v_mov_b32_e32 v54, v0
	v_mov_b32_e32 v55, v0
	v_mov_b32_e32 v8, v0
	v_mov_b32_e32 v9, v0
	v_mov_b32_e32 v10, v0
	v_mov_b32_e32 v11, v0
	v_mov_b32_e32 v12, v0
	v_mov_b32_e32 v13, v0
	v_mov_b32_e32 v14, v0
	v_mov_b32_e32 v15, v0
	v_mov_b32_e32 v24, v0
	v_mov_b32_e32 v25, v0
	v_mov_b32_e32 v26, v0
	v_mov_b32_e32 v27, v0
	v_mov_b32_e32 v28, v0
	v_mov_b32_e32 v29, v0
	v_mov_b32_e32 v30, v0
	v_mov_b32_e32 v31, v0
	v_mov_b32_e32 v40, v0
	v_mov_b32_e32 v41, v0
	v_mov_b32_e32 v42, v0
	v_mov_b32_e32 v43, v0
	v_mov_b32_e32 v44, v0
	v_mov_b32_e32 v45, v0
	v_mov_b32_e32 v46, v0
	v_mov_b32_e32 v47, v0
	v_mov_b32_e32 v56, v0
	v_mov_b32_e32 v57, v0
	v_mov_b32_e32 v58, v0
	v_mov_b32_e32 v59, v0
	v_mov_b32_e32 v60, v0
	v_mov_b32_e32 v61, v0
	v_mov_b32_e32 v62, v0
	v_mov_b32_e32 v63, v0
	v_mov_b32_e32 v64, v0
	v_mov_b32_e32 v65, v0
	v_mov_b32_e32 v66, v0
	v_mov_b32_e32 v67, v0
	v_mov_b32_e32 v68, v0
	v_mov_b32_e32 v69, v0
	v_mov_b32_e32 v70, v0
	v_mov_b32_e32 v71, v0
	v_mov_b32_e32 v80, v0
	v_mov_b32_e32 v81, v0
	v_mov_b32_e32 v82, v0
	v_mov_b32_e32 v83, v0
	v_mov_b32_e32 v84, v0
	v_mov_b32_e32 v85, v0
	v_mov_b32_e32 v86, v0
	v_mov_b32_e32 v87, v0
	v_mov_b32_e32 v96, v0
	v_mov_b32_e32 v97, v0
	v_mov_b32_e32 v98, v0
	v_mov_b32_e32 v99, v0
	v_mov_b32_e32 v100, v0
	v_mov_b32_e32 v101, v0
	v_mov_b32_e32 v102, v0
	v_mov_b32_e32 v103, v0
	v_mov_b32_e32 v112, v0
	v_mov_b32_e32 v113, v0
	v_mov_b32_e32 v114, v0
	v_mov_b32_e32 v115, v0
	v_mov_b32_e32 v116, v0
	v_mov_b32_e32 v117, v0
	v_mov_b32_e32 v118, v0
	v_mov_b32_e32 v119, v0
	v_mov_b32_e32 v72, v0
	v_mov_b32_e32 v73, v0
	v_mov_b32_e32 v74, v0
	v_mov_b32_e32 v75, v0
	v_mov_b32_e32 v76, v0
	v_mov_b32_e32 v77, v0
	v_mov_b32_e32 v78, v0
	v_mov_b32_e32 v79, v0
	v_mov_b32_e32 v88, v0
	v_mov_b32_e32 v89, v0
	v_mov_b32_e32 v90, v0
	v_mov_b32_e32 v91, v0
	v_mov_b32_e32 v92, v0
	v_mov_b32_e32 v93, v0
	v_mov_b32_e32 v94, v0
	v_mov_b32_e32 v95, v0
	v_mov_b32_e32 v104, v0
	v_mov_b32_e32 v105, v0
	v_mov_b32_e32 v106, v0
	v_mov_b32_e32 v107, v0
	v_mov_b32_e32 v108, v0
	v_mov_b32_e32 v109, v0
	v_mov_b32_e32 v110, v0
	v_mov_b32_e32 v111, v0
	v_mov_b32_e32 v120, v0
	v_mov_b32_e32 v121, v0
	v_mov_b32_e32 v122, v0
	v_mov_b32_e32 v123, v0
	v_mov_b32_e32 v124, v0
	v_mov_b32_e32 v125, v0
	v_mov_b32_e32 v126, v0
	v_mov_b32_e32 v127, v0
	s_waitcnt vmcnt(0)

; template <class Epi, class Sched, bool ALIGN_EPI = false, bool SP2 = false>
; __device__ __forceinline__ void gemm_phase(PG8_LAS unsigned char* lds, const Gemm g, const Sched& S, const Epi& E) {
;     ...
;         const char* nA = has_next ? (const char*)g.A + (size_t)nxt.pm * tstep : cA; const char* nB = has_next ? (const char*)g.Bt + (size_t)nxt.pn * tstep : cB;
;         for (int t = 0; t < nt; t += 2) {
;             const bool last = (t == nt - 2);
;             const char* a1 = cA + (size_t)(t + 1) * kstep;
;             const char* a2 = last ? nA : cA + (size_t)(t + 2) * kstep; const char* b2 = last ? nB : cB + (size_t)(t + 2) * kstep;
;     ...
;         for (int a = 0; a < 2; ++a)
; #pragma unroll
;             for (int b = 0; b < 2; ++b)
; #pragma unroll
;                 for (int m = 0; m < 4; ++m)
; #pragma unroll
;                     for (int n = 0; n < 2; ++n) acc[a][b][m][n] = (f32x4){0.f, 0.f, 0.f, 0.f};
.LBB0_330:
	s_ashr_i32 s45, s44, 31
	s_lshl_b64 s[46:47], s[44:45], 20
	s_add_u32 s46, s12, s46
	s_addc_u32 s47, s13, s47
	s_and_b64 s[48:49], s[40:41], exec
	s_cselect_b32 s45, s47, s75
	s_cselect_b32 s59, s46, s74
	s_ashr_i32 s43, s42, 31
	s_lshl_b64 s[48:49], s[42:43], 20
	s_add_u32 s48, s14, s48
	s_addc_u32 s49, s0, s49
	s_and_b64 s[78:79], s[40:41], exec
	s_cselect_b32 s43, s49, s77
	s_cselect_b32 s63, s48, s76
	s_add_u32 s74, s74, 0x80080
	s_addc_u32 s75, s75, 0
	s_add_u32 s71, s76, 0x100
	v_mov_b32_e32 v0, 0
	s_addc_u32 s80, s77, 0
	s_mov_b32 s81, -2
	v_mov_b32_e32 v1, v0
	v_mov_b32_e32 v2, v0
	v_mov_b32_e32 v3, v0
	v_mov_b32_e32 v12, v0
	v_mov_b32_e32 v13, v0
	v_mov_b32_e32 v14, v0
	v_mov_b32_e32 v15, v0
	v_mov_b32_e32 v20, v0
	v_mov_b32_e32 v21, v0
	v_mov_b32_e32 v22, v0
	v_mov_b32_e32 v23, v0
	v_mov_b32_e32 v28, v0
	v_mov_b32_e32 v29, v0
	v_mov_b32_e32 v30, v0
	v_mov_b32_e32 v31, v0
	v_mov_b32_e32 v36, v0
	v_mov_b32_e32 v37, v0
	v_mov_b32_e32 v38, v0
	v_mov_b32_e32 v39, v0
	v_mov_b32_e32 v44, v0
	v_mov_b32_e32 v45, v0
	v_mov_b32_e32 v46, v0
	v_mov_b32_e32 v47, v0
	v_mov_b32_e32 v52, v0
	v_mov_b32_e32 v53, v0
	v_mov_b32_e32 v54, v0
	v_mov_b32_e32 v55, v0
	v_mov_b32_e32 v60, v0
	v_mov_b32_e32 v61, v0
	v_mov_b32_e32 v62, v0
	v_mov_b32_e32 v63, v0
	v_mov_b32_e32 v4, v0
	v_mov_b32_e32 v5, v0
	v_mov_b32_e32 v6, v0
	v_mov_b32_e32 v7, v0
	v_mov_b32_e32 v8, v0
	v_mov_b32_e32 v9, v0
	v_mov_b32_e32 v10, v0
	v_mov_b32_e32 v11, v0
	v_mov_b32_e32 v16, v0
	v_mov_b32_e32 v17, v0
	v_mov_b32_e32 v18, v0
	v_mov_b32_e32 v19, v0
	v_mov_b32_e32 v24, v0
	v_mov_b32_e32 v25, v0
	v_mov_b32_e32 v26, v0
	v_mov_b32_e32 v27, v0
	v_mov_b32_e32 v32, v0
	v_mov_b32_e32 v33, v0
	v_mov_b32_e32 v34, v0
	v_mov_b32_e32 v35, v0
	v_mov_b32_e32 v40, v0
	v_mov_b32_e32 v41, v0
	v_mov_b32_e32 v42, v0
	v_mov_b32_e32 v43, v0
	v_mov_b32_e32 v48, v0
	v_mov_b32_e32 v49, v0
	v_mov_b32_e32 v50, v0
	v_mov_b32_e32 v51, v0
	v_mov_b32_e32 v56, v0
	v_mov_b32_e32 v57, v0
	v_mov_b32_e32 v58, v0
	v_mov_b32_e32 v59, v0
	v_mov_b32_e32 v68, v0
	v_mov_b32_e32 v69, v0
	v_mov_b32_e32 v70, v0
	v_mov_b32_e32 v71, v0
	v_mov_b32_e32 v76, v0
	v_mov_b32_e32 v77, v0
	v_mov_b32_e32 v78, v0
	v_mov_b32_e32 v79, v0
	v_mov_b32_e32 v84, v0
	v_mov_b32_e32 v85, v0
	v_mov_b32_e32 v86, v0
	v_mov_b32_e32 v87, v0
	v_mov_b32_e32 v92, v0
	v_mov_b32_e32 v93, v0
	v_mov_b32_e32 v94, v0
	v_mov_b32_e32 v95, v0
	v_mov_b32_e32 v100, v0
	v_mov_b32_e32 v101, v0
	v_mov_b32_e32 v102, v0
	v_mov_b32_e32 v103, v0
	v_mov_b32_e32 v108, v0
	v_mov_b32_e32 v109, v0
	v_mov_b32_e32 v110, v0
	v_mov_b32_e32 v111, v0
	v_mov_b32_e32 v120, v0
	v_mov_b32_e32 v121, v0
	v_mov_b32_e32 v122, v0
	v_mov_b32_e32 v123, v0
	v_mov_b32_e32 v124, v0
	v_mov_b32_e32 v125, v0
	v_mov_b32_e32 v126, v0
	v_mov_b32_e32 v127, v0
	v_mov_b32_e32 v64, v0
	v_mov_b32_e32 v65, v0
	v_mov_b32_e32 v66, v0
	v_mov_b32_e32 v67, v0
	v_mov_b32_e32 v72, v0
	v_mov_b32_e32 v73, v0
	v_mov_b32_e32 v74, v0
	v_mov_b32_e32 v75, v0
	v_mov_b32_e32 v80, v0
	v_mov_b32_e32 v81, v0
	v_mov_b32_e32 v82, v0
	v_mov_b32_e32 v83, v0
	v_mov_b32_e32 v88, v0
	v_mov_b32_e32 v89, v0
	v_mov_b32_e32 v90, v0
	v_mov_b32_e32 v91, v0
	v_mov_b32_e32 v96, v0
	v_mov_b32_e32 v97, v0
	v_mov_b32_e32 v98, v0
	v_mov_b32_e32 v99, v0
	v_mov_b32_e32 v104, v0
	v_mov_b32_e32 v105, v0
	v_mov_b32_e32 v106, v0
	v_mov_b32_e32 v107, v0
	v_mov_b32_e32 v112, v0
	v_mov_b32_e32 v113, v0
	v_mov_b32_e32 v114, v0
	v_mov_b32_e32 v115, v0
	v_mov_b32_e32 v116, v0
	v_mov_b32_e32 v117, v0
	v_mov_b32_e32 v118, v0
	v_mov_b32_e32 v119, v0
	s_waitcnt vmcnt(0)
